# attention loop: hoisted LDS/global address math, permlane max exchange, deferred row-sum exchange, plain f32 row-sum adds
# speedup vs baseline: 1.1633x; 1.0108x over previous
; DI int get_tid() { int t = (int)__builtin_amdgcn_workitem_id_x(); asm volatile("" : "+v"(t)); return t; }
; DI f32x16 zero16() { f32x16 z; _Pragma("unroll") for (int i = 0; i < 16; ++i) z[i] = 0.f; return z; }
; DI void attn_item(const Params& p, const bf16_t* Qbase  , int bh, int q0, int nkeys, int out_row0, unsigned char* smem) {
;     ...
;     const int tid = get_tid(), lane = tid & 63, wave = tid >> 6, li = lane & 31, lh = lane >> 5;
;     const bf16_t* Kg = (const bf16_t*)(p.ws + WS_K) + (size_t)bh * NKEY * 96;
;     const bf16_t* Vg = (const bf16_t*)(p.ws + WS_VT) + (size_t)bh * 64 * NKEY;
;     bf16x8 qf[6];
; #pragma unroll
;     for (int ks = 0; ks < 6; ++ks) qf[ks] = ld8(Qbase + (size_t)(q0 + 32 * wave + li) * 96 + 16 * ks + 8 * lh);
;     u32x4 rk[3], rv[2];
;     auto gload = [&](int kt) {
; #pragma unroll
;         for (int i = 0; i < 3; ++i) { int id = tid + 256 * i; rk[i] = *(const u32x4*)(Kg + (size_t)kt * 64 * 96 + id * 8); }
; #pragma unroll
;         for (int i = 0; i < 2; ++i) { int id = tid + 256 * i, v = id >> 3, kc = id & 7; rv[i] = *(const u32x4*)(Vg + (size_t)v * NKEY + kt * 64 + kc * 8); }
;     };
;     auto sstore = [&](int buf) {
; #pragma unroll
;         for (int i = 0; i < 3; ++i) { int id = tid + 256 * i, key = id / 12, dc = id - key * 12; *(u32x4*)(Ks + (buf * 64 + key) * KS + dc * 8) = rk[i]; }
; #pragma unroll
;         for (int i = 0; i < 2; ++i) { int id = tid + 256 * i, v = id >> 3, kc = id & 7; bf16_t* d = Vs + (buf * 64 + v) * VS + kc * 8;
;             u32x2 lo, hi; lo.x = rv[i].x; lo.y = rv[i].y; hi.x = rv[i].z; hi.y = rv[i].w; *(u32x2*)d = lo; *(u32x2*)(d + 4) = hi; }
;     };
;     const int nkt = nkeys >> 6;
;     const float scl = 0.10206207261596577f * 1.4426950408889634f;
;     f32x16 o0 = zero16(), o1 = zero16(); float m = -1e30f, l = 0.f;
;     __syncthreads();
;     gload(0); sstore(0); __syncthreads();
.LBB0_412:
	s_andn2_b64 vcc, exec, s[0:1]
	s_cbranch_vccnz .LBB0_422
	s_add_i32 s1, s15, 0xfffffe00
	s_lshr_b32 s0, s1, 5
	s_mul_i32 s8, s0, 0xc0000
	v_readlane_b32 s10, v252, 8
	s_mul_hi_u32 s9, s0, 0xc0000
	v_readlane_b32 s11, v252, 9
	s_add_u32 s8, s10, s8
	s_addc_u32 s9, s11, s9
	s_lshl_b32 s10, s15, 7
	v_mov_b32_e32 v0, v168
	s_and_b32 s12, s10, 0xf80
	s_mul_i32 s18, s0, 0xcc000
	v_and_b32_e32 v1, 31, v0
	v_ashrrev_i32_e32 v4, 1, v0
	v_and_b32_e32 v113, 0xffffffe0, v4
	v_or_b32_e32 v115, s12, v1
	v_add_u32_e32 v6, v115, v113
	v_mov_b64_e32 v[4:5], s[8:9]
	s_movk_i32 s8, 0xc0
	v_lshlrev_b32_e32 v12, 3, v0
	v_bfe_u32 v2, v0, 5, 1
	v_readlane_b32 s10, v253, 28
	v_mad_i64_i32 v[4:5], s[8:9], v6, s8, v[4:5]
	v_add_u32_e32 v6, 0x800, v12
	s_mul_hi_u32 s13, s0, 0xcc000
	v_readlane_b32 s11, v253, 29
	s_add_u32 s10, s10, s18
	v_lshlrev_b32_e32 v24, 4, v2
	v_mov_b32_e32 v25, v3
	v_ashrrev_i32_e32 v13, 31, v12
	v_ashrrev_i32_e32 v7, 31, v6
	s_addc_u32 s11, s11, s13
	v_lshl_add_u64 v[4:5], v[4:5], 0, v[24:25]
	v_lshlrev_b64 v[26:27], 1, v[12:13]
	v_lshlrev_b64 v[28:29], 1, v[6:7]
	global_load_dwordx4 v[88:91], v[4:5], off
	global_load_dwordx4 v[84:87], v[4:5], off offset:32
	global_load_dwordx4 v[80:83], v[4:5], off offset:64
	global_load_dwordx4 v[76:79], v[4:5], off offset:96
	global_load_dwordx4 v[72:75], v[4:5], off offset:128
	global_load_dwordx4 v[68:71], v[4:5], off offset:160
	v_lshl_add_u64 v[4:5], s[10:11], 0, v[26:27]
	v_lshl_add_u64 v[8:9], s[10:11], 0, v[28:29]
	s_waitcnt vmcnt(63) expcnt(7) lgkmcnt(15)
	s_barrier
	global_load_dwordx4 v[4:7], v[4:5], off
	s_nop 0
	global_load_dwordx4 v[8:11], v[8:9], off
	s_mul_i32 s36, s0, 0x88000
	v_readlane_b32 s8, v253, 30
	s_mul_hi_u32 s19, s0, 0x88000
	v_readlane_b32 s9, v253, 31
	s_add_u32 s8, s8, s36
	s_addc_u32 s9, s9, s19
	v_add_u32_e32 v12, 0x1000, v12
	v_ashrrev_i32_e32 v13, 31, v12
	v_ashrrev_i32_e32 v129, 3, v0
	v_mov_b64_e32 v[20:21], s[8:9]
	s_movk_i32 s12, 0x2200
	v_lshlrev_b32_e32 v16, 4, v0
	v_lshlrev_b64 v[30:31], 1, v[12:13]
	v_mad_i64_i32 v[14:15], s[8:9], v129, s12, v[20:21]
	v_and_b32_e32 v32, 0x70, v16
	v_mov_b32_e32 v33, v3
	v_add_u32_e32 v34, 0x100, v0
	v_lshl_add_u64 v[12:13], s[10:11], 0, v[30:31]
	v_lshl_add_u64 v[16:17], v[14:15], 0, v[32:33]
	v_ashrrev_i32_e32 v130, 3, v34
	global_load_dwordx4 v[12:15], v[12:13], off
	s_nop 0
	global_load_dwordx4 v[16:19], v[16:17], off
	v_mad_i64_i32 v[20:21], s[8:9], v130, s12, v[20:21]
	v_lshl_add_u64 v[20:21], v[20:21], 0, v[32:33]
	global_load_dwordx4 v[20:23], v[20:21], off
	v_mul_hi_i32 v25, v0, s33
	v_lshrrev_b32_e32 v33, 31, v25
	v_ashrrev_i32_e32 v25, 1, v25
	v_mul_hi_i32 v35, v34, s33
	v_add_u32_e32 v131, v25, v33
	v_lshrrev_b32_e32 v25, 31, v35
	v_ashrrev_i32_e32 v33, 1, v35
	v_mad_u64_u32 v[38:39], s[8:9], v131, -12, v[0:1]
	v_add_u32_e32 v132, v33, v25
	v_add_u32_e32 v36, 0x200, v0
	v_lshl_add_u32 v112, v38, 4, 0
	v_mad_u64_u32 v[34:35], s[8:9], v132, -12, v[34:35]
	s_movk_i32 s10, 0xd0
	v_mad_u64_u32 v[38:39], s[8:9], v131, s10, v[112:113]
	v_lshl_add_u32 v114, v34, 4, 0
	v_mul_hi_i32 v0, v36, s33
	v_mad_u64_u32 v[34:35], s[8:9], v132, s10, v[114:115]
	v_add_u32_e32 v134, 0, v32
	s_waitcnt vmcnt(4)
	ds_write_b128 v38, v[4:7]
	s_waitcnt vmcnt(3)
	ds_write_b128 v34, v[8:11]
	v_lshrrev_b32_e32 v4, 31, v0
	v_ashrrev_i32_e32 v0, 1, v0
	v_add_u32_e32 v133, v0, v4
	v_mad_u64_u32 v[4:5], s[8:9], v133, -12, v[36:37]
	v_lshl_add_u32 v116, v4, 4, 0
	v_mad_u64_u32 v[4:5], s[8:9], v133, s10, v[116:117]
	s_movk_i32 s8, 0x88
	s_nop 0
	v_mul_lo_u32 v0, v129, s8
	s_movk_i32 s9, 0x6800
	v_add3_u32 v0, v134, v0, s9
	s_add_u32 s10, s36, 0x39ea080
	s_addc_u32 s11, s19, 0
	v_lshlrev_b32_e32 v2, 3, v2
	v_add_u32_e32 v135, 0, v24
	v_mov_b32_e32 v6, v3
	v_mov_b32_e32 v7, v3
	v_mov_b32_e32 v8, v3
	v_mov_b32_e32 v9, v3
	s_waitcnt vmcnt(2)
	ds_write_b128 v4, v[12:15]
	s_waitcnt vmcnt(1)
	ds_write2_b64 v0, v[16:17], v[18:19] offset1:1
	v_mul_lo_u32 v0, v130, s8
	v_add3_u32 v0, v134, v0, s9
	v_and_b32_e32 v4, 64, v182
	s_waitcnt vmcnt(0)
	ds_write2_b64 v0, v[20:21], v[22:23] offset1:1
	v_xor_b32_e32 v0, 32, v182
	v_add_u32_e32 v4, 64, v4
	v_cmp_lt_i32_e32 vcc, v0, v4
	v_mov_b64_e32 v[4:5], s[10:11]
	v_mad_i64_i32 v[118:119], s[10:11], v129, s12, v[4:5]
	v_mad_i64_i32 v[120:121], s[10:11], v130, s12, v[4:5]
	s_add_u32 s10, s18, 0x954d000
	s_addc_u32 s11, s13, 0
	v_mov_b32_e32 v18, v3
	v_mov_b32_e32 v19, v3
	v_cndmask_b32_e32 v0, v182, v0, vcc
	v_or_b32_e32 v118, v118, v32
	v_or_b32_e32 v120, v120, v32
	v_lshl_add_u64 v[122:123], s[10:11], 0, v[26:27]
	v_lshl_add_u64 v[124:125], s[10:11], 0, v[28:29]
	v_lshl_add_u64 v[126:127], s[10:11], 0, v[30:31]
	v_mov_b32_e32 v4, v3
	v_mov_b32_e32 v5, v3
	v_mov_b32_e32 v10, v3
	v_mov_b32_e32 v11, v3
	v_mov_b32_e32 v12, v3
	v_mov_b32_e32 v13, v3
	v_mov_b32_e32 v14, v3
	v_mov_b32_e32 v15, v3
	v_mov_b32_e32 v16, v3
	v_mov_b32_e32 v17, v3
	v_mov_b64_e32 v[34:35], v[18:19]
	s_movk_i32 s37, 0xd0
	s_mov_b32 s8, 0
	v_lshlrev_b32_e32 v128, 2, v0
	v_sub_u32_e32 v117, v135, v2
	v_mov_b32_e32 v0, 0
	v_mov_b32_e32 v136, 0xf149f2ca
	v_mov_b64_e32 v[32:33], v[16:17]
	v_mov_b64_e32 v[30:31], v[14:15]
	v_mov_b64_e32 v[28:29], v[12:13]
	v_mov_b64_e32 v[26:27], v[10:11]
	v_mov_b64_e32 v[24:25], v[8:9]
	v_mov_b64_e32 v[22:23], v[6:7]
	v_mov_b64_e32 v[20:21], v[4:5]
	s_waitcnt lgkmcnt(0)
	s_barrier
	v_mad_u32_u24 v154, v1, s37, v135
	s_movk_i32 s12, 0x88
	v_mad_u32_u24 v155, v1, s12, v117
	v_add_u32_e32 v155, 0x6800, v155
	v_add_u32_e32 v156, 0x1000, v155
	v_mad_u32_u24 v157, v131, s37, v112
	v_mad_u32_u24 v158, v132, s37, v114
	v_mad_u32_u24 v159, v133, s37, v116
	v_mad_u32_u24 v160, v129, s12, v134
	v_add_u32_e32 v160, 0x6800, v160
	v_mad_u32_u24 v161, v130, s12, v134
	v_add_u32_e32 v161, 0x6800, v161
; #define MFMA(a, b, c) __builtin_amdgcn_mfma_f32_32x32x16_bf16((a), (b), (c), 0, 0, 0)
; DI f32x16 zero16() { f32x16 z; _Pragma("unroll") for (int i = 0; i < 16; ++i) z[i] = 0.f; return z; }
; DI void attn_item(const Params& p, const bf16_t* Qbase  , int bh, int q0, int nkeys, int out_row0, unsigned char* smem) {
;     ...
;     for (int kt = 0; kt < nkt; ++kt) {
;         const int buf = kt & 1;
;         if (kt + 1 < nkt) gload(kt + 1);
;         __builtin_amdgcn_sched_barrier(0);
;         f32x16 s0 = zero16(), s1 = zero16();
;         const bf16_t* kb = Ks + (buf * 64 + li) * KS + 8 * lh;
; #pragma unroll
;         for (int ks = 0; ks < 6; ++ks) { s0 = MFMA(ld8(kb + 16 * ks), qf[ks], s0); s1 = MFMA(ld8(kb + 32 * KS + 16 * ks), qf[ks], s1); }
;         float mx = fmaxf(s0[0], s1[0]);
; #pragma unroll
;         for (int r = 1; r < 16; ++r) mx = fmaxf(fmaxf(mx, s0[r]), s1[r]);
;         mx = fmaxf(mx, __shfl_xor(mx, 32));
;         const float mn = fmaxf(m, mx);
;         if (__any(mn > m)) {
;             const float corr = __builtin_amdgcn_exp2f((m - mn) * scl);
;             l *= corr;
; #pragma unroll
;             for (int r = 0; r < 16; ++r) { o0[r] *= corr; o1[r] *= corr; }
;             m = mn;
;         }
.LBB0_414:
	global_load_dwordx4 v[108:111], v122, s[26:27]
	global_load_dwordx4 v[104:107], v124, s[26:27]
	global_load_dwordx4 v[100:103], v126, s[26:27]
	global_load_dwordx4 v[96:99], v118, s[26:27]
	global_load_dwordx4 v[92:95], v120, s[26:27]
	s_and_b32 s9, s8, 64
	s_mul_i32 s12, s9, 0xd0
	v_add_u32_e32 v137, s12, v154
	ds_read_b128 v[202:205], v137
	ds_read_b128 v[206:209], v137 offset:6656
	ds_read_b128 v[210:213], v137 offset:32
	ds_read_b128 v[214:217], v137 offset:6688
	ds_read_b128 v[218:221], v137 offset:64
	s_waitcnt lgkmcnt(4)
	v_mfma_f32_32x32x16_bf16 v[36:51], v[202:205], v[88:91], 0
	ds_read_b128 v[202:205], v137 offset:6720
	s_waitcnt lgkmcnt(4)
	v_mfma_f32_32x32x16_bf16 v[52:67], v[206:209], v[88:91], 0
	ds_read_b128 v[206:209], v137 offset:96
	s_waitcnt lgkmcnt(4)
	v_mfma_f32_32x32x16_bf16 v[36:51], v[210:213], v[84:87], v[36:51]
	ds_read_b128 v[210:213], v137 offset:6752
	s_waitcnt lgkmcnt(4)
	v_mfma_f32_32x32x16_bf16 v[52:67], v[214:217], v[84:87], v[52:67]
	ds_read_b128 v[214:217], v137 offset:128
	s_waitcnt lgkmcnt(4)
	v_mfma_f32_32x32x16_bf16 v[36:51], v[218:221], v[80:83], v[36:51]
	ds_read_b128 v[218:221], v137 offset:6784
	s_waitcnt lgkmcnt(4)
	v_mfma_f32_32x32x16_bf16 v[52:67], v[202:205], v[80:83], v[52:67]
	ds_read_b128 v[202:205], v137 offset:160
	s_waitcnt lgkmcnt(4)
	v_mfma_f32_32x32x16_bf16 v[36:51], v[206:209], v[76:79], v[36:51]
	ds_read_b128 v[206:209], v137 offset:6816
	s_waitcnt lgkmcnt(4)
	v_mfma_f32_32x32x16_bf16 v[52:67], v[210:213], v[76:79], v[52:67]
	s_waitcnt lgkmcnt(3)
	v_mfma_f32_32x32x16_bf16 v[36:51], v[214:217], v[72:75], v[36:51]
	s_waitcnt lgkmcnt(2)
	v_mfma_f32_32x32x16_bf16 v[52:67], v[218:221], v[72:75], v[52:67]
	s_waitcnt lgkmcnt(1)
	v_mfma_f32_32x32x16_bf16 v[36:51], v[202:205], v[68:71], v[36:51]
	s_waitcnt lgkmcnt(0)
	v_mfma_f32_32x32x16_bf16 v[52:67], v[206:209], v[68:71], v[52:67]
	s_mul_i32 s13, s9, 0x88
	v_add_u32_e32 v148, s13, v155
	v_add_u32_e32 v151, s13, v156
	s_nop 9
	v_max3_f32 v137, v36, v37, v38
	v_max3_f32 v139, v52, v53, v54
	v_max3_f32 v137, v137, v39, v40
	v_max3_f32 v139, v139, v55, v56
	v_max3_f32 v137, v137, v41, v42
	v_max3_f32 v139, v139, v57, v58
	v_max3_f32 v137, v137, v43, v44
	v_max3_f32 v139, v139, v59, v60
	v_max3_f32 v137, v137, v45, v46
	v_max3_f32 v139, v139, v61, v62
	v_max3_f32 v137, v137, v47, v48
	v_max3_f32 v139, v139, v63, v64
	v_max3_f32 v137, v137, v49, v50
	v_max3_f32 v139, v139, v65, v66
	v_max3_f32 v137, v137, v51, v139
	v_max_f32_e32 v137, v137, v67
	v_mov_b32_e32 v140, v137
	v_mov_b32_e32 v141, v137
	s_nop 1
	v_permlane32_swap_b32_e32 v140, v141
	v_max3_f32 v139, v137, v140, v141
	v_max_f32_e32 v137, v136, v139
	v_cmp_gt_f32_e32 vcc, v137, v136
	s_cbranch_vccz .Lattn_keep
	v_sub_f32_e32 v136, v136, v137
	v_mul_f32_e32 v136, 0x3e16c740, v136
	v_exp_f32_e32 v136, v136
	s_nop 0
	v_pk_mul_f32 v[4:5], v[4:5], v[136:137] op_sel_hi:[1,0]
	v_pk_mul_f32 v[6:7], v[6:7], v[136:137] op_sel_hi:[1,0]
	v_pk_mul_f32 v[8:9], v[8:9], v[136:137] op_sel_hi:[1,0]
	v_pk_mul_f32 v[10:11], v[10:11], v[136:137] op_sel_hi:[1,0]
	v_pk_mul_f32 v[12:13], v[12:13], v[136:137] op_sel_hi:[1,0]
	v_pk_mul_f32 v[14:15], v[14:15], v[136:137] op_sel_hi:[1,0]
	v_pk_mul_f32 v[16:17], v[16:17], v[136:137] op_sel_hi:[1,0]
	v_pk_mul_f32 v[18:19], v[18:19], v[136:137] op_sel_hi:[1,0]
	v_pk_mul_f32 v[20:21], v[20:21], v[136:137] op_sel_hi:[1,0]
	v_pk_mul_f32 v[22:23], v[22:23], v[136:137] op_sel_hi:[1,0]
	v_pk_mul_f32 v[24:25], v[24:25], v[136:137] op_sel_hi:[1,0]
	v_pk_mul_f32 v[26:27], v[26:27], v[136:137] op_sel_hi:[1,0]
	v_pk_mul_f32 v[28:29], v[28:29], v[136:137] op_sel_hi:[1,0]
	v_pk_mul_f32 v[30:31], v[30:31], v[136:137] op_sel_hi:[1,0]
	v_pk_mul_f32 v[32:33], v[32:33], v[136:137] op_sel_hi:[1,0]
	v_pk_mul_f32 v[34:35], v[34:35], v[136:137] op_sel_hi:[1,0]
	v_mul_f32_e32 v0, v0, v136
; #define MFMA(a, b, c) __builtin_amdgcn_mfma_f32_32x32x16_bf16((a), (b), (c), 0, 0, 0)
; DI void attn_item(const Params& p, const bf16_t* Qbase  , int bh, int q0, int nkeys, int out_row0, unsigned char* smem) {
;     ...
;         const float nb = -m * scl;
;         float sum0 = 0.f, sum1 = 0.f;
; #pragma unroll
;         for (int r = 0; r < 16; ++r) { s0[r] = __builtin_amdgcn_exp2f(fmaf(s0[r], scl, nb)); s1[r] = __builtin_amdgcn_exp2f(fmaf(s1[r], scl, nb)); sum0 += s0[r]; sum1 += s1[r]; }
;         float sum = sum0 + sum1;
;         sum += __shfl_xor(sum, 32);
;         l += sum;
;         bf16x8 pf[2][2];
;         pf[0][0] = pack8(s0[0], s0[1], s0[2], s0[3], s0[4], s0[5], s0[6], s0[7]); pf[0][1] = pack8(s0[8], s0[9], s0[10], s0[11], s0[12], s0[13], s0[14], s0[15]);
;         pf[1][0] = pack8(s1[0], s1[1], s1[2], s1[3], s1[4], s1[5], s1[6], s1[7]); pf[1][1] = pack8(s1[8], s1[9], s1[10], s1[11], s1[12], s1[13], s1[14], s1[15]);
;         const bf16_t* vb = Vs + (buf * 64 + li) * VS + 4 * lh;
; #pragma unroll
;         for (int j = 0; j < 2; ++j)
; #pragma unroll
;             for (int s = 0; s < 2; ++s) {
;                 const int ko = 32 * j + 16 * s;
;                 o0 = MFMA(ld4x2(vb + ko, vb + ko + 8), pf[j][s], o0);
;                 o1 = MFMA(ld4x2(vb + 32 * VS + ko, vb + 32 * VS + ko + 8), pf[j][s], o1);
;             }
;         __builtin_amdgcn_sched_barrier(0);
;         if (kt + 1 < nkt) sstore(buf ^ 1);
;         __syncthreads();
;     }
;     const float inv = 1.f / l;
.Lattn_keep:
	v_mul_f32_e32 v136, 0xbe16c740, v137
	v_fmamk_f32 v36, v36, 0x3e16c740, v136
	v_fmamk_f32 v37, v37, 0x3e16c740, v136
	v_exp_f32_e32 v36, v36
	v_fmamk_f32 v38, v38, 0x3e16c740, v136
	v_exp_f32_e32 v37, v37
	v_fmamk_f32 v39, v39, 0x3e16c740, v136
	v_exp_f32_e32 v38, v38
	v_fmamk_f32 v40, v40, 0x3e16c740, v136
	v_exp_f32_e32 v39, v39
	v_fmamk_f32 v41, v41, 0x3e16c740, v136
	v_exp_f32_e32 v40, v40
	v_fmamk_f32 v42, v42, 0x3e16c740, v136
	v_exp_f32_e32 v41, v41
	v_fmamk_f32 v43, v43, 0x3e16c740, v136
	v_exp_f32_e32 v42, v42
	v_fmamk_f32 v44, v44, 0x3e16c740, v136
	v_exp_f32_e32 v43, v43
	v_fmamk_f32 v45, v45, 0x3e16c740, v136
	v_exp_f32_e32 v44, v44
	v_fmamk_f32 v46, v46, 0x3e16c740, v136
	v_exp_f32_e32 v45, v45
	v_fmamk_f32 v47, v47, 0x3e16c740, v136
	v_exp_f32_e32 v46, v46
	v_fmamk_f32 v48, v48, 0x3e16c740, v136
	v_exp_f32_e32 v47, v47
	v_fmamk_f32 v49, v49, 0x3e16c740, v136
	v_exp_f32_e32 v48, v48
	v_fmamk_f32 v50, v50, 0x3e16c740, v136
	v_exp_f32_e32 v49, v49
	v_fmamk_f32 v51, v51, 0x3e16c740, v136
	v_exp_f32_e32 v50, v50
	v_fmamk_f32 v52, v52, 0x3e16c740, v136
	v_exp_f32_e32 v51, v51
	v_fmamk_f32 v53, v53, 0x3e16c740, v136
	v_exp_f32_e32 v52, v52
	v_fmamk_f32 v54, v54, 0x3e16c740, v136
	v_exp_f32_e32 v53, v53
	v_fmamk_f32 v55, v55, 0x3e16c740, v136
	v_exp_f32_e32 v54, v54
	v_fmamk_f32 v56, v56, 0x3e16c740, v136
	v_exp_f32_e32 v55, v55
	v_fmamk_f32 v57, v57, 0x3e16c740, v136
	v_exp_f32_e32 v56, v56
	v_fmamk_f32 v58, v58, 0x3e16c740, v136
	v_exp_f32_e32 v57, v57
	v_fmamk_f32 v59, v59, 0x3e16c740, v136
	v_exp_f32_e32 v58, v58
	v_fmamk_f32 v60, v60, 0x3e16c740, v136
	v_exp_f32_e32 v59, v59
	v_fmamk_f32 v61, v61, 0x3e16c740, v136
	v_exp_f32_e32 v60, v60
	v_fmamk_f32 v62, v62, 0x3e16c740, v136
	v_exp_f32_e32 v61, v61
	v_fmamk_f32 v63, v63, 0x3e16c740, v136
	v_exp_f32_e32 v62, v62
	v_fmamk_f32 v64, v64, 0x3e16c740, v136
	v_exp_f32_e32 v63, v63
	v_fmamk_f32 v65, v65, 0x3e16c740, v136
	v_exp_f32_e32 v64, v64
	v_fmamk_f32 v66, v66, 0x3e16c740, v136
	v_exp_f32_e32 v65, v65
	v_fmamk_f32 v67, v67, 0x3e16c740, v136
	v_exp_f32_e32 v66, v66
	v_exp_f32_e32 v67, v67
	v_add_f32_e32 v138, v36, v37
	v_add_f32_e32 v139, v44, v45
	v_add_f32_e32 v152, v52, v53
	v_add_f32_e32 v153, v60, v61
	v_add_f32_e32 v138, v138, v38
	v_add_f32_e32 v139, v139, v46
	v_add_f32_e32 v152, v152, v54
	v_add_f32_e32 v153, v153, v62
	v_add_f32_e32 v138, v138, v39
	v_add_f32_e32 v139, v139, v47
	v_add_f32_e32 v152, v152, v55
	v_add_f32_e32 v153, v153, v63
	v_add_f32_e32 v138, v138, v40
	v_add_f32_e32 v139, v139, v48
	v_add_f32_e32 v152, v152, v56
	v_add_f32_e32 v153, v153, v64
	v_add_f32_e32 v138, v138, v41
	v_add_f32_e32 v139, v139, v49
	v_add_f32_e32 v152, v152, v57
	v_add_f32_e32 v153, v153, v65
	v_add_f32_e32 v138, v138, v42
	v_add_f32_e32 v139, v139, v50
	v_add_f32_e32 v152, v152, v58
	v_add_f32_e32 v153, v153, v66
	v_add_f32_e32 v138, v138, v43
	v_add_f32_e32 v139, v139, v51
	v_add_f32_e32 v152, v152, v59
	v_add_f32_e32 v153, v153, v67
	v_cvt_pk_bf16_f32 v140, v52, v53
	v_cvt_pk_bf16_f32 v141, v54, v55
	v_cvt_pk_bf16_f32 v142, v56, v57
	v_cvt_pk_bf16_f32 v143, v58, v59
	v_cvt_pk_bf16_f32 v144, v60, v61
	v_cvt_pk_bf16_f32 v145, v62, v63
	v_cvt_pk_bf16_f32 v146, v64, v65
	v_cvt_pk_bf16_f32 v147, v66, v67
	ds_read2_b64 v[52:55], v148 offset1:2
	ds_read2_b64 v[56:59], v151 offset0:32 offset1:34
	ds_read2_b64 v[60:63], v148 offset0:4 offset1:6
	ds_read2_b64 v[64:67], v151 offset0:36 offset1:38
	v_cvt_pk_bf16_f32 v36, v36, v37
	v_cvt_pk_bf16_f32 v37, v38, v39
	v_cvt_pk_bf16_f32 v38, v40, v41
	v_cvt_pk_bf16_f32 v39, v42, v43
	v_cvt_pk_bf16_f32 v40, v44, v45
	v_cvt_pk_bf16_f32 v41, v46, v47
	v_cvt_pk_bf16_f32 v42, v48, v49
	v_cvt_pk_bf16_f32 v43, v50, v51
	v_add_f32_e32 v138, v138, v139
	v_add_f32_e32 v152, v152, v153
	v_add_f32_e32 v138, v138, v152
	v_add_f32_e32 v0, v0, v138
	s_waitcnt lgkmcnt(3)
	v_mfma_f32_32x32x16_bf16 v[4:19], v[52:55], v[36:39], v[4:19]
	ds_read2_b64 v[52:55], v148 offset0:8 offset1:10
	s_waitcnt lgkmcnt(3)
	v_mfma_f32_32x32x16_bf16 v[20:35], v[56:59], v[36:39], v[20:35]
	ds_read2_b64 v[56:59], v151 offset0:40 offset1:42
	s_waitcnt lgkmcnt(3)
	v_mfma_f32_32x32x16_bf16 v[4:19], v[60:63], v[40:43], v[4:19]
	ds_read2_b64 v[60:63], v148 offset0:12 offset1:14
	s_waitcnt lgkmcnt(3)
	v_mfma_f32_32x32x16_bf16 v[20:35], v[64:67], v[40:43], v[20:35]
	ds_read2_b64 v[64:67], v151 offset0:44 offset1:46
	s_waitcnt lgkmcnt(3)
	v_mfma_f32_32x32x16_bf16 v[4:19], v[52:55], v[140:143], v[4:19]
	s_waitcnt lgkmcnt(2)
	v_mfma_f32_32x32x16_bf16 v[20:35], v[56:59], v[140:143], v[20:35]
	s_waitcnt lgkmcnt(1)
	v_mfma_f32_32x32x16_bf16 v[4:19], v[60:63], v[144:147], v[4:19]
	s_waitcnt lgkmcnt(0)
	v_mfma_f32_32x32x16_bf16 v[20:35], v[64:67], v[144:147], v[20:35]
	s_xor_b32 s9, s9, 64
	s_mul_i32 s12, s9, 0xd0
	s_mul_i32 s13, s9, 0x88
	v_add_u32_e32 v36, s12, v157
	s_waitcnt vmcnt(4)
	ds_write_b128 v36, v[108:111]
	v_add_u32_e32 v36, s12, v158
	s_waitcnt vmcnt(3)
	ds_write_b128 v36, v[104:107]
	v_add_u32_e32 v36, s12, v159
	s_waitcnt vmcnt(2)
	ds_write_b128 v36, v[100:103]
	v_add_u32_e32 v36, s13, v160
	s_waitcnt vmcnt(1)
	ds_write2_b64 v36, v[96:97], v[98:99] offset1:1
	v_add_u32_e32 v36, s13, v161
	s_add_i32 s8, s8, 64
	v_add_u32_e32 v122, 0x3000, v122
	v_add_u32_e32 v124, 0x3000, v124
	v_add_u32_e32 v126, 0x3000, v126
	v_add_u32_e32 v118, 0x80, v118
	v_add_u32_e32 v120, 0x80, v120
	s_mov_b64 s[10:11], 0x3000
	s_movk_i32 s12, 0x88
	s_movk_i32 s13, 0xd0
	s_movk_i32 s37, 0xd0
	s_movk_i32 s71, 0x88
	s_mov_b64 s[68:69], 0x3000
	s_waitcnt vmcnt(0)
	ds_write2_b64 v36, v[92:93], v[94:95] offset1:1
	s_waitcnt lgkmcnt(0)
	s_barrier
	s_cmpk_eq_i32 s8, 0x10c0
	s_cbranch_scc1 .Lattn_exit
	v_mov_b32_e32 v136, v137
	s_branch .LBB0_414
.Lattn_exit:
	v_mov_b32_e32 v140, v0
	v_mov_b32_e32 v141, v0
	s_nop 1
	v_permlane32_swap_b32_e32 v140, v141
	v_add_f32_e32 v0, v140, v141
